# chunk-local phase: the gMLP blocks (320..447) hand their 4th round of S5 chunk tasks to the item-less blocks 448..511 (2 extra tasks per wave), 512-block grid only
# speedup vs baseline: 1.0098x; 1.0042x over previous
.LBB0_1006:
	s_movk_i32 s43, 0x1000
	s_or_b64 exec, exec, s[70:71]
	v_mov_b32_e32 v14, v231
	ds_read_b64 v[10:11], v229 offset:63760
	ds_read_b64 v[6:7], v229 offset:63760
	ds_read_b64 v[12:13], v229 offset:63760
	ds_read_b64 v[8:9], v229 offset:63760
	s_waitcnt lgkmcnt(0)
	ds_read_b64 v[2:3], v229 offset:63760
	ds_read_b64 v[0:1], v229 offset:63760
	ds_read_b64 v[4:5], v229 offset:63760
	v_ashrrev_i32_e32 v15, 6, v14
	s_mov_b32 s0, s76
	s_nop 0
	v_lshl_add_u32 v55, s0, 2, v15
	v_cmp_gt_i32_e32 vcc, s94, v55
	s_mov_b64 s[0:1], exec
	v_readlane_b32 s78, v255, 13
	s_and_b64 s[2:3], s[0:1], vcc
	s_movk_i32 s22, 0x110
	s_movk_i32 s23, 0x2200
	s_movk_i32 s24, 0x840
	s_movk_i32 s25, 0x210
	s_mov_b32 s26, 0x8800
	s_mov_b32 s27, 0x1780000
	s_movk_i32 s46, 0x1600
	s_mov_b32 s47, 0x84000
	s_mov_b32 s48, 0x58000
	s_mov_b32 s49, 0x2c000
	s_mov_b32 s51, s87
	s_mov_b64 s[52:53], 0x40000
	s_mov_b64 s[54:55], 0x1200000
	s_mov_b64 s[56:57], 0x2ad4000
	s_mov_b64 s[58:59], 0x4ad4000
	s_mov_b64 s[60:61], 0x80
	s_mov_b64 s[62:63], 0x5ad4000
	s_mov_b64 s[64:65], 0x9ad4000
	s_mov_b64 s[66:67], 0x1c00
	s_mov_b32 s68, 0x3b800000
	s_mov_b64 s[70:71], 0x1800
	s_mov_b32 s69, s82
	v_readlane_b32 s79, v255, 14
	s_mov_b64 exec, s[2:3]
	s_cbranch_execz .LBB0_1011
	s_movk_i32 s2, 0x2c00
	v_mul_lo_u32 v67, v15, s2
	s_mov_b64 s[2:3], 0x2a54000
	v_lshl_add_u64 v[46:47], v[12:13], 0, s[2:3]
	s_mov_b64 s[2:3], 0x2a94000
	v_lshl_add_u64 v[48:49], v[8:9], 0, s[2:3]
	s_mov_b64 s[2:3], 0x2a44000
	v_lshl_add_u64 v[50:51], v[6:7], 0, s[2:3]
	v_readlane_b32 s2, v255, 9
	v_and_b32_e32 v228, 48, v14
	v_and_b32_e32 v59, 63, v14
	s_lshl_b32 s4, s2, 5
	s_waitcnt lgkmcnt(0)
	v_lshl_add_u64 v[4:5], v[4:5], 0, v[228:229]
	s_mov_b64 s[2:3], 0xef54000
	v_lshl_add_u64 v[52:53], v[4:5], 0, s[2:3]
	v_lshlrev_b32_e32 v6, 3, v59
	v_lshl_add_u32 v84, v59, 5, v67
	s_movk_i32 s2, 0xffe4
	v_mov_b32_e32 v7, v229
	v_and_b32_e32 v9, 15, v14
	v_mad_i32_i24 v54, v59, s2, v84
	v_lshl_add_u64 v[2:3], v[2:3], 0, v[6:7]
	s_mov_b64 s[2:3], 0xe754000
	v_lshl_add_u64 v[56:57], v[2:3], 0, s[2:3]
	v_or_b32_e32 v2, v67, v228
	v_lshlrev_b32_e32 v228, 2, v9
	v_lshlrev_b32_e32 v4, 10, v14
	v_lshl_add_u64 v[0:1], v[0:1], 0, v[228:229]
	s_mov_b64 s[2:3], 0xa2d4000
	v_lshl_add_u64 v[44:45], v[10:11], 0, s[62:63]
	v_lshlrev_b32_e32 v10, 7, v9
	v_and_b32_e32 v4, 0xf800, v4
	v_and_b32_e32 v8, 8, v6
	v_lshrrev_b32_e32 v3, 2, v14
	v_lshl_add_u64 v[60:61], v[0:1], 0, s[2:3]
	v_mul_u32_u24_e32 v0, 0x110, v9
	v_and_b32_e32 v58, 12, v3
	s_mov_b64 s[2:3], 0
	v_lshlrev_b32_e32 v85, 1, v10
	v_lshlrev_b32_e32 v62, 2, v4
	v_lshlrev_b32_e32 v64, 2, v8
	v_add_u32_e32 v86, v2, v0
	s_mov_b32 s18, s77
	s_mov_b32 s19, s86
	s_mov_b32 s20, 0
	s_cmp_eq_u32 s77, 0x800
	s_cbranch_scc0 .Ls5l_ctl_done
	s_cmpk_lt_u32 s76, 0x1c0
	s_cbranch_scc0 .Ls5l_ctl_idle
	s_cmpk_lt_u32 s76, 0x140
	s_cbranch_scc1 .Ls5l_ctl_done
	s_movk_i32 s19, 0x17ff
	s_branch .Ls5l_ctl_done
.Ls5l_ctl_idle:
	s_mov_b32 s20, 1
.Ls5l_ctl_done:
.LBB0_1008:
	v_bfe_u32 v87, v55, 4, 1
	v_and_b32_e32 v63, 15, v55
	v_lshlrev_b32_e32 v88, 4, v87
	v_or3_b32 v4, v88, s4, v63
	v_lshl_or_b32 v2, v4, 6, v59
	v_lshlrev_b32_e32 v228, 1, v2
	v_lshl_add_u64 v[0:1], v[228:229], 2, v[50:51]
	v_lshlrev_b32_e32 v228, 4, v2
	v_and_b32_e32 v68, 0xffffffe0, v55
	global_load_dwordx2 v[70:71], v[0:1], off
	v_lshlrev_b64 v[0:1], 2, v[228:229]
	v_ashrrev_i32_e32 v69, 31, v68
	v_lshl_add_u64 v[2:3], v[46:47], 0, v[0:1]
	v_lshl_add_u64 v[0:1], v[48:49], 0, v[0:1]
	v_lshl_or_b32 v228, v4, 12, v85
	v_lshlrev_b64 v[72:73], 13, v[68:69]
	global_load_dwordx4 v[32:35], v[2:3], off offset:48
	global_load_dwordx4 v[36:39], v[2:3], off offset:32
	global_load_dwordx4 v[40:43], v[2:3], off offset:16
	global_load_dwordx4 v[90:93], v[2:3], off
	global_load_dwordx4 v[12:15], v[0:1], off offset:48
	global_load_dwordx4 v[16:19], v[0:1], off offset:32
	global_load_dwordx4 v[20:23], v[0:1], off offset:16
	global_load_dwordx4 v[24:27], v[0:1], off
	v_lshl_add_u64 v[0:1], v[52:53], 0, v[228:229]
	v_lshl_add_u64 v[72:73], v[44:45], 0, v[72:73]
	v_lshlrev_b32_e32 v228, 6, v63
	v_lshlrev_b32_e32 v66, 4, v63
	v_lshl_add_u64 v[72:73], v[72:73], 0, v[228:229]
	v_mov_b32_e32 v63, v229
	v_lshl_add_u64 v[72:73], v[72:73], 0, v[62:63]
	v_mov_b32_e32 v65, v229
	global_load_dwordx4 v[28:31], v[0:1], off
	global_load_dwordx4 v[8:11], v[0:1], off offset:64
	global_load_dwordx4 v[4:7], v[0:1], off offset:128
	s_nop 0
	global_load_dwordx4 v[0:3], v[0:1], off offset:192
	v_lshl_add_u64 v[76:77], v[72:73], 0, v[64:65]
	global_load_dwordx4 v[72:75], v[76:77], off offset:16
	s_nop 0
	global_load_dwordx4 v[76:79], v[76:77], off
	s_mov_b32 s5, 0
	v_cmp_eq_u32_e32 vcc, 0, v87
	s_mov_b32 s6, 28
	s_waitcnt vmcnt(0)
	ds_write_b128 v84, v[76:79]
	ds_write_b128 v84, v[72:75] offset:16
	v_and_b32_e32 v208, 31, v59
	v_sub_u32_e32 v209, 31, v208
	v_mov_b32_e32 v217, 0x110
	v_mov_b32_e32 v210, 0xfffffef0
	v_cndmask_b32_e32 v208, v209, v208, vcc
	v_lshrrev_b32_e32 v209, 5, v59
	v_add_u32_e32 v211, 0x20f0, v54
	v_cndmask_b32_e32 v217, v210, v217, vcc
	v_lshlrev_b32_e32 v209, 2, v209
	v_cndmask_b32_e32 v216, v211, v54, vcc
	v_lshl_add_u32 v218, v208, 6, v67
	v_add_u32_e32 v218, v218, v209
	ds_read_b32 v200, v218
	ds_read_b32 v201, v218 offset:8
	ds_read_b32 v202, v218 offset:16
	ds_read_b32 v203, v218 offset:24
	ds_read_b32 v204, v218 offset:32
	ds_read_b32 v205, v218 offset:40
	ds_read_b32 v206, v218 offset:48
	ds_read_b32 v207, v218 offset:56
	v_permlane32_swap_b32_e32 v90, v91
	v_permlane32_swap_b32_e32 v92, v93
	v_permlane32_swap_b32_e32 v40, v41
	v_permlane32_swap_b32_e32 v42, v43
	v_permlane32_swap_b32_e32 v36, v37
	v_permlane32_swap_b32_e32 v38, v39
	v_permlane32_swap_b32_e32 v32, v33
	v_permlane32_swap_b32_e32 v34, v35
	v_permlane32_swap_b32_e32 v24, v25
	v_permlane32_swap_b32_e32 v26, v27
	v_permlane32_swap_b32_e32 v20, v21
	v_permlane32_swap_b32_e32 v22, v23
	v_permlane32_swap_b32_e32 v16, v17
	v_permlane32_swap_b32_e32 v18, v19
	v_permlane32_swap_b32_e32 v12, v13
	v_permlane32_swap_b32_e32 v14, v15
	s_waitcnt lgkmcnt(0)
	s_nop 1
	v_mfma_f32_32x32x2_f32 v[136:151], v200, v90, 0
	v_mfma_f32_32x32x2_f32 v[136:151], v201, v92, v[136:151]
	v_mfma_f32_32x32x2_f32 v[136:151], v202, v40, v[136:151]
	v_mfma_f32_32x32x2_f32 v[136:151], v203, v42, v[136:151]
	v_mfma_f32_32x32x2_f32 v[136:151], v204, v36, v[136:151]
	v_mfma_f32_32x32x2_f32 v[136:151], v205, v38, v[136:151]
	v_mfma_f32_32x32x2_f32 v[136:151], v206, v32, v[136:151]
	v_mfma_f32_32x32x2_f32 v[136:151], v207, v34, v[136:151]
	v_mfma_f32_32x32x2_f32 v[152:167], v200, v91, 0
	v_mfma_f32_32x32x2_f32 v[152:167], v201, v93, v[152:167]
	v_mfma_f32_32x32x2_f32 v[152:167], v202, v41, v[152:167]
	v_mfma_f32_32x32x2_f32 v[152:167], v203, v43, v[152:167]
	v_mfma_f32_32x32x2_f32 v[152:167], v204, v37, v[152:167]
	v_mfma_f32_32x32x2_f32 v[152:167], v205, v39, v[152:167]
	v_mfma_f32_32x32x2_f32 v[152:167], v206, v33, v[152:167]
	v_mfma_f32_32x32x2_f32 v[152:167], v207, v35, v[152:167]
	v_mfma_f32_32x32x2_f32 v[168:183], v200, v24, 0
	v_mfma_f32_32x32x2_f32 v[168:183], v201, v26, v[168:183]
	v_mfma_f32_32x32x2_f32 v[168:183], v202, v20, v[168:183]
	v_mfma_f32_32x32x2_f32 v[168:183], v203, v22, v[168:183]
	v_mfma_f32_32x32x2_f32 v[168:183], v204, v16, v[168:183]
	v_mfma_f32_32x32x2_f32 v[168:183], v205, v18, v[168:183]
	v_mfma_f32_32x32x2_f32 v[168:183], v206, v12, v[168:183]
	v_mfma_f32_32x32x2_f32 v[168:183], v207, v14, v[168:183]
	v_mfma_f32_32x32x2_f32 v[184:199], v200, v25, 0
	v_mfma_f32_32x32x2_f32 v[184:199], v201, v27, v[184:199]
	v_mfma_f32_32x32x2_f32 v[184:199], v202, v21, v[184:199]
	v_mfma_f32_32x32x2_f32 v[184:199], v203, v23, v[184:199]
	v_mfma_f32_32x32x2_f32 v[184:199], v204, v17, v[184:199]
	v_mfma_f32_32x32x2_f32 v[184:199], v205, v19, v[184:199]
	v_mfma_f32_32x32x2_f32 v[184:199], v206, v13, v[184:199]
	v_mfma_f32_32x32x2_f32 v[184:199], v207, v15, v[184:199]
	s_nop 15
	s_nop 3
	v_permlane32_swap_b32_e32 v136, v152
	v_permlane32_swap_b32_e32 v137, v153
	v_permlane32_swap_b32_e32 v138, v154
	v_permlane32_swap_b32_e32 v139, v155
	v_permlane32_swap_b32_e32 v140, v156
	v_permlane32_swap_b32_e32 v141, v157
	v_permlane32_swap_b32_e32 v142, v158
	v_permlane32_swap_b32_e32 v143, v159
	v_permlane32_swap_b32_e32 v144, v160
	v_permlane32_swap_b32_e32 v145, v161
	v_permlane32_swap_b32_e32 v146, v162
	v_permlane32_swap_b32_e32 v147, v163
	v_permlane32_swap_b32_e32 v148, v164
	v_permlane32_swap_b32_e32 v149, v165
	v_permlane32_swap_b32_e32 v150, v166
	v_permlane32_swap_b32_e32 v151, v167
	v_permlane32_swap_b32_e32 v168, v184
	v_permlane32_swap_b32_e32 v169, v185
	v_permlane32_swap_b32_e32 v170, v186
	v_permlane32_swap_b32_e32 v171, v187
	v_permlane32_swap_b32_e32 v172, v188
	v_permlane32_swap_b32_e32 v173, v189
	v_permlane32_swap_b32_e32 v174, v190
	v_permlane32_swap_b32_e32 v175, v191
	v_permlane32_swap_b32_e32 v176, v192
	v_permlane32_swap_b32_e32 v177, v193
	v_permlane32_swap_b32_e32 v178, v194
	v_permlane32_swap_b32_e32 v179, v195
	v_permlane32_swap_b32_e32 v180, v196
	v_permlane32_swap_b32_e32 v181, v197
	v_permlane32_swap_b32_e32 v182, v198
	v_permlane32_swap_b32_e32 v183, v199
	v_mov_b32_e32 v32, 0
	v_mov_b32_e32 v33, 0
	v_mul_f32_e32 v208, v71, v33
	v_mul_f32_e32 v209, v71, v32
	v_fma_f32 v32, v70, v32, -v208
	v_fma_f32 v33, v70, v33, v209
	v_add_f32_e32 v32, v32, v136
	v_add_f32_e32 v33, v33, v168
	v_cvt_pk_bf16_f32 v210, v32, v33
	ds_write_b32 v216, v210 offset:2048
	v_add_u32_e32 v216, v216, v217
	v_mul_f32_e32 v208, v71, v33
	v_mul_f32_e32 v209, v71, v32
	v_fma_f32 v32, v70, v32, -v208
	v_fma_f32 v33, v70, v33, v209
	v_add_f32_e32 v32, v32, v137
	v_add_f32_e32 v33, v33, v169
	v_cvt_pk_bf16_f32 v210, v32, v33
	ds_write_b32 v216, v210 offset:2048
	v_add_u32_e32 v216, v216, v217
	v_mul_f32_e32 v208, v71, v33
	v_mul_f32_e32 v209, v71, v32
	v_fma_f32 v32, v70, v32, -v208
	v_fma_f32 v33, v70, v33, v209
	v_add_f32_e32 v32, v32, v138
	v_add_f32_e32 v33, v33, v170
	v_cvt_pk_bf16_f32 v210, v32, v33
	ds_write_b32 v216, v210 offset:2048
	v_add_u32_e32 v216, v216, v217
	v_mul_f32_e32 v208, v71, v33
	v_mul_f32_e32 v209, v71, v32
	v_fma_f32 v32, v70, v32, -v208
	v_fma_f32 v33, v70, v33, v209
	v_add_f32_e32 v32, v32, v139
	v_add_f32_e32 v33, v33, v171
	v_cvt_pk_bf16_f32 v210, v32, v33
	ds_write_b32 v216, v210 offset:2048
	v_add_u32_e32 v216, v216, v217
	v_mul_f32_e32 v208, v71, v33
	v_mul_f32_e32 v209, v71, v32
	v_fma_f32 v32, v70, v32, -v208
	v_fma_f32 v33, v70, v33, v209
	v_add_f32_e32 v32, v32, v152
	v_add_f32_e32 v33, v33, v184
	v_cvt_pk_bf16_f32 v210, v32, v33
	ds_write_b32 v216, v210 offset:2048
	v_add_u32_e32 v216, v216, v217
	v_mul_f32_e32 v208, v71, v33
	v_mul_f32_e32 v209, v71, v32
	v_fma_f32 v32, v70, v32, -v208
	v_fma_f32 v33, v70, v33, v209
	v_add_f32_e32 v32, v32, v153
	v_add_f32_e32 v33, v33, v185
	v_cvt_pk_bf16_f32 v210, v32, v33
	ds_write_b32 v216, v210 offset:2048
	v_add_u32_e32 v216, v216, v217
	v_mul_f32_e32 v208, v71, v33
	v_mul_f32_e32 v209, v71, v32
	v_fma_f32 v32, v70, v32, -v208
	v_fma_f32 v33, v70, v33, v209
	v_add_f32_e32 v32, v32, v154
	v_add_f32_e32 v33, v33, v186
	v_cvt_pk_bf16_f32 v210, v32, v33
	ds_write_b32 v216, v210 offset:2048
	v_add_u32_e32 v216, v216, v217
	v_mul_f32_e32 v208, v71, v33
	v_mul_f32_e32 v209, v71, v32
	v_fma_f32 v32, v70, v32, -v208
	v_fma_f32 v33, v70, v33, v209
	v_add_f32_e32 v32, v32, v155
	v_add_f32_e32 v33, v33, v187
	v_cvt_pk_bf16_f32 v210, v32, v33
	ds_write_b32 v216, v210 offset:2048
	v_add_u32_e32 v216, v216, v217
	v_mul_f32_e32 v208, v71, v33
	v_mul_f32_e32 v209, v71, v32
	v_fma_f32 v32, v70, v32, -v208
	v_fma_f32 v33, v70, v33, v209
	v_add_f32_e32 v32, v32, v140
	v_add_f32_e32 v33, v33, v172
	v_cvt_pk_bf16_f32 v210, v32, v33
	ds_write_b32 v216, v210 offset:2048
	v_add_u32_e32 v216, v216, v217
	v_mul_f32_e32 v208, v71, v33
	v_mul_f32_e32 v209, v71, v32
	v_fma_f32 v32, v70, v32, -v208
	v_fma_f32 v33, v70, v33, v209
	v_add_f32_e32 v32, v32, v141
	v_add_f32_e32 v33, v33, v173
	v_cvt_pk_bf16_f32 v210, v32, v33
	ds_write_b32 v216, v210 offset:2048
	v_add_u32_e32 v216, v216, v217
	v_mul_f32_e32 v208, v71, v33
	v_mul_f32_e32 v209, v71, v32
	v_fma_f32 v32, v70, v32, -v208
	v_fma_f32 v33, v70, v33, v209
	v_add_f32_e32 v32, v32, v142
	v_add_f32_e32 v33, v33, v174
	v_cvt_pk_bf16_f32 v210, v32, v33
	ds_write_b32 v216, v210 offset:2048
	v_add_u32_e32 v216, v216, v217
	v_mul_f32_e32 v208, v71, v33
	v_mul_f32_e32 v209, v71, v32
	v_fma_f32 v32, v70, v32, -v208
	v_fma_f32 v33, v70, v33, v209
	v_add_f32_e32 v32, v32, v143
	v_add_f32_e32 v33, v33, v175
	v_cvt_pk_bf16_f32 v210, v32, v33
	ds_write_b32 v216, v210 offset:2048
	v_add_u32_e32 v216, v216, v217
	v_mul_f32_e32 v208, v71, v33
	v_mul_f32_e32 v209, v71, v32
	v_fma_f32 v32, v70, v32, -v208
	v_fma_f32 v33, v70, v33, v209
	v_add_f32_e32 v32, v32, v156
	v_add_f32_e32 v33, v33, v188
	v_cvt_pk_bf16_f32 v210, v32, v33
	ds_write_b32 v216, v210 offset:2048
	v_add_u32_e32 v216, v216, v217
	v_mul_f32_e32 v208, v71, v33
	v_mul_f32_e32 v209, v71, v32
	v_fma_f32 v32, v70, v32, -v208
	v_fma_f32 v33, v70, v33, v209
	v_add_f32_e32 v32, v32, v157
	v_add_f32_e32 v33, v33, v189
	v_cvt_pk_bf16_f32 v210, v32, v33
	ds_write_b32 v216, v210 offset:2048
	v_add_u32_e32 v216, v216, v217
	v_mul_f32_e32 v208, v71, v33
	v_mul_f32_e32 v209, v71, v32
	v_fma_f32 v32, v70, v32, -v208
	v_fma_f32 v33, v70, v33, v209
	v_add_f32_e32 v32, v32, v158
	v_add_f32_e32 v33, v33, v190
	v_cvt_pk_bf16_f32 v210, v32, v33
	ds_write_b32 v216, v210 offset:2048
	v_add_u32_e32 v216, v216, v217
	v_mul_f32_e32 v208, v71, v33
	v_mul_f32_e32 v209, v71, v32
	v_fma_f32 v32, v70, v32, -v208
	v_fma_f32 v33, v70, v33, v209
	v_add_f32_e32 v32, v32, v159
	v_add_f32_e32 v33, v33, v191
	v_cvt_pk_bf16_f32 v210, v32, v33
	ds_write_b32 v216, v210 offset:2048
	v_add_u32_e32 v216, v216, v217
	v_mul_f32_e32 v208, v71, v33
	v_mul_f32_e32 v209, v71, v32
	v_fma_f32 v32, v70, v32, -v208
	v_fma_f32 v33, v70, v33, v209
	v_add_f32_e32 v32, v32, v144
	v_add_f32_e32 v33, v33, v176
	v_cvt_pk_bf16_f32 v210, v32, v33
	ds_write_b32 v216, v210 offset:2048
	v_add_u32_e32 v216, v216, v217
	v_mul_f32_e32 v208, v71, v33
	v_mul_f32_e32 v209, v71, v32
	v_fma_f32 v32, v70, v32, -v208
	v_fma_f32 v33, v70, v33, v209
	v_add_f32_e32 v32, v32, v145
	v_add_f32_e32 v33, v33, v177
	v_cvt_pk_bf16_f32 v210, v32, v33
	ds_write_b32 v216, v210 offset:2048
	v_add_u32_e32 v216, v216, v217
	v_mul_f32_e32 v208, v71, v33
	v_mul_f32_e32 v209, v71, v32
	v_fma_f32 v32, v70, v32, -v208
	v_fma_f32 v33, v70, v33, v209
	v_add_f32_e32 v32, v32, v146
	v_add_f32_e32 v33, v33, v178
	v_cvt_pk_bf16_f32 v210, v32, v33
	ds_write_b32 v216, v210 offset:2048
	v_add_u32_e32 v216, v216, v217
	v_mul_f32_e32 v208, v71, v33
	v_mul_f32_e32 v209, v71, v32
	v_fma_f32 v32, v70, v32, -v208
	v_fma_f32 v33, v70, v33, v209
	v_add_f32_e32 v32, v32, v147
	v_add_f32_e32 v33, v33, v179
	v_cvt_pk_bf16_f32 v210, v32, v33
	ds_write_b32 v216, v210 offset:2048
	v_add_u32_e32 v216, v216, v217
	v_mul_f32_e32 v208, v71, v33
	v_mul_f32_e32 v209, v71, v32
	v_fma_f32 v32, v70, v32, -v208
	v_fma_f32 v33, v70, v33, v209
	v_add_f32_e32 v32, v32, v160
	v_add_f32_e32 v33, v33, v192
	v_cvt_pk_bf16_f32 v210, v32, v33
	ds_write_b32 v216, v210 offset:2048
	v_add_u32_e32 v216, v216, v217
	v_mul_f32_e32 v208, v71, v33
	v_mul_f32_e32 v209, v71, v32
	v_fma_f32 v32, v70, v32, -v208
	v_fma_f32 v33, v70, v33, v209
	v_add_f32_e32 v32, v32, v161
	v_add_f32_e32 v33, v33, v193
	v_cvt_pk_bf16_f32 v210, v32, v33
	ds_write_b32 v216, v210 offset:2048
	v_add_u32_e32 v216, v216, v217
	v_mul_f32_e32 v208, v71, v33
	v_mul_f32_e32 v209, v71, v32
	v_fma_f32 v32, v70, v32, -v208
	v_fma_f32 v33, v70, v33, v209
	v_add_f32_e32 v32, v32, v162
	v_add_f32_e32 v33, v33, v194
	v_cvt_pk_bf16_f32 v210, v32, v33
	ds_write_b32 v216, v210 offset:2048
	v_add_u32_e32 v216, v216, v217
	v_mul_f32_e32 v208, v71, v33
	v_mul_f32_e32 v209, v71, v32
	v_fma_f32 v32, v70, v32, -v208
	v_fma_f32 v33, v70, v33, v209
	v_add_f32_e32 v32, v32, v163
	v_add_f32_e32 v33, v33, v195
	v_cvt_pk_bf16_f32 v210, v32, v33
	ds_write_b32 v216, v210 offset:2048
	v_add_u32_e32 v216, v216, v217
	v_mul_f32_e32 v208, v71, v33
	v_mul_f32_e32 v209, v71, v32
	v_fma_f32 v32, v70, v32, -v208
	v_fma_f32 v33, v70, v33, v209
	v_add_f32_e32 v32, v32, v148
	v_add_f32_e32 v33, v33, v180
	v_cvt_pk_bf16_f32 v210, v32, v33
	ds_write_b32 v216, v210 offset:2048
	v_add_u32_e32 v216, v216, v217
	v_mul_f32_e32 v208, v71, v33
	v_mul_f32_e32 v209, v71, v32
	v_fma_f32 v32, v70, v32, -v208
	v_fma_f32 v33, v70, v33, v209
	v_add_f32_e32 v32, v32, v149
	v_add_f32_e32 v33, v33, v181
	v_cvt_pk_bf16_f32 v210, v32, v33
	ds_write_b32 v216, v210 offset:2048
	v_add_u32_e32 v216, v216, v217
	v_mul_f32_e32 v208, v71, v33
	v_mul_f32_e32 v209, v71, v32
	v_fma_f32 v32, v70, v32, -v208
	v_fma_f32 v33, v70, v33, v209
	v_add_f32_e32 v32, v32, v150
	v_add_f32_e32 v33, v33, v182
	v_cvt_pk_bf16_f32 v210, v32, v33
	ds_write_b32 v216, v210 offset:2048
	v_add_u32_e32 v216, v216, v217
	v_mul_f32_e32 v208, v71, v33
	v_mul_f32_e32 v209, v71, v32
	v_fma_f32 v32, v70, v32, -v208
	v_fma_f32 v33, v70, v33, v209
	v_add_f32_e32 v32, v32, v151
	v_add_f32_e32 v33, v33, v183
	v_cvt_pk_bf16_f32 v210, v32, v33
	ds_write_b32 v216, v210 offset:2048
	v_add_u32_e32 v216, v216, v217
	v_mul_f32_e32 v208, v71, v33
	v_mul_f32_e32 v209, v71, v32
	v_fma_f32 v32, v70, v32, -v208
	v_fma_f32 v33, v70, v33, v209
	v_add_f32_e32 v32, v32, v164
	v_add_f32_e32 v33, v33, v196
	v_cvt_pk_bf16_f32 v210, v32, v33
	ds_write_b32 v216, v210 offset:2048
	v_add_u32_e32 v216, v216, v217
	v_mul_f32_e32 v208, v71, v33
	v_mul_f32_e32 v209, v71, v32
	v_fma_f32 v32, v70, v32, -v208
	v_fma_f32 v33, v70, v33, v209
	v_add_f32_e32 v32, v32, v165
	v_add_f32_e32 v33, v33, v197
	v_cvt_pk_bf16_f32 v210, v32, v33
	ds_write_b32 v216, v210 offset:2048
	v_add_u32_e32 v216, v216, v217
	v_mul_f32_e32 v208, v71, v33
	v_mul_f32_e32 v209, v71, v32
	v_fma_f32 v32, v70, v32, -v208
	v_fma_f32 v33, v70, v33, v209
	v_add_f32_e32 v32, v32, v166
	v_add_f32_e32 v33, v33, v198
	v_cvt_pk_bf16_f32 v210, v32, v33
	ds_write_b32 v216, v210 offset:2048
	v_add_u32_e32 v216, v216, v217
	v_mul_f32_e32 v208, v71, v33
	v_mul_f32_e32 v209, v71, v32
	v_fma_f32 v32, v70, v32, -v208
	v_fma_f32 v33, v70, v33, v209
	v_add_f32_e32 v32, v32, v167
	v_add_f32_e32 v33, v33, v199
	v_cvt_pk_bf16_f32 v210, v32, v33
	ds_write_b32 v216, v210 offset:2048
	s_movk_i32 s5, 0xffef
	v_and_or_b32 v12, v55, s5, v88
	v_ashrrev_i32_e32 v13, 31, v12
	v_lshlrev_b64 v[12:13], 9, v[12:13]
	v_lshl_add_u64 v[12:13], v[56:57], 0, v[12:13]
	global_store_dwordx2 v[12:13], v[32:33], off
	ds_read_b128 v[12:15], v86 offset:2048
	ds_read_b128 v[20:23], v86 offset:2112
	ds_read_b128 v[16:19], v86 offset:6400
	v_lshlrev_b32_e32 v228, 13, v87
	v_add_u32_e32 v55, s18, v55
	v_cmp_lt_i32_e32 vcc, s19, v55
	s_or_b64 s[2:3], vcc, s[2:3]
	s_waitcnt lgkmcnt(2)
	v_mfma_f32_16x16x32_bf16 v[12:15], v[12:15], v[28:31], 0
	s_waitcnt lgkmcnt(1)
	v_mfma_f32_16x16x32_bf16 v[12:15], v[20:23], v[8:11], v[12:15]
	ds_read_b128 v[20:23], v86 offset:6464
	s_waitcnt lgkmcnt(1)
	v_mfma_f32_16x16x32_bf16 v[16:19], v[16:19], v[28:31], 0
	s_waitcnt lgkmcnt(0)
	v_mfma_f32_16x16x32_bf16 v[8:11], v[20:23], v[8:11], v[16:19]
	s_nop 5
	ds_read_b128 v[16:19], v86 offset:2176
	s_waitcnt lgkmcnt(0)
	v_mfma_f32_16x16x32_bf16 v[12:15], v[16:19], v[4:7], v[12:15]
	ds_read_b128 v[16:19], v86 offset:6528
	s_waitcnt lgkmcnt(0)
	v_mfma_f32_16x16x32_bf16 v[4:7], v[16:19], v[4:7], v[8:11]
	s_nop 2
	ds_read_b128 v[8:11], v86 offset:2240
	s_waitcnt lgkmcnt(0)
	v_mfma_f32_16x16x32_bf16 v[8:11], v[8:11], v[0:3], v[12:15]
	s_nop 2
	ds_read_b128 v[12:15], v86 offset:6592
	s_waitcnt lgkmcnt(0)
	v_mfma_f32_16x16x32_bf16 v[0:3], v[12:15], v[0:3], v[4:7]
	s_nop 2
	v_lshl_add_u64 v[4:5], v[228:229], 0, v[68:69]
	v_or_b32_e32 v4, v4, v58
	v_lshlrev_b32_e32 v228, 2, v66
	v_lshl_add_u64 v[6:7], v[60:61], 0, v[228:229]
	v_lshlrev_b64 v[4:5], 10, v[4:5]
	v_lshl_add_u64 v[12:13], v[6:7], 0, v[4:5]
	global_store_dword v[12:13], v8, off
	global_store_dword v[12:13], v9, off offset:1024
	global_store_dword v[12:13], v10, off offset:2048
	global_store_dword v[12:13], v11, off offset:3072
	v_or_b32_e32 v8, 0x4000, v4
	v_mov_b32_e32 v9, v5
	v_lshl_add_u64 v[8:9], v[6:7], 0, v[8:9]
	global_store_dword v[8:9], v0, off
	v_or_b32_e32 v8, 0x4400, v4
	v_mov_b32_e32 v9, v5
	v_lshl_add_u64 v[8:9], v[6:7], 0, v[8:9]
	global_store_dword v[8:9], v1, off
	v_or_b32_e32 v0, 0x4800, v4
	v_mov_b32_e32 v1, v5
	v_lshl_add_u64 v[0:1], v[6:7], 0, v[0:1]
	v_or_b32_e32 v4, 0x4c00, v4
	global_store_dword v[0:1], v2, off
	v_lshl_add_u64 v[0:1], v[6:7], 0, v[4:5]
	global_store_dword v[0:1], v3, off
	s_andn2_b64 exec, exec, s[2:3]
	s_cbranch_execnz .LBB0_1008
	s_cmp_eq_u32 s20, 1
	s_cbranch_scc0 .LBB0_1011
	s_mov_b32 s20, 0
	s_movk_i32 s18, 0x100
	s_movk_i32 s19, 0x1eff
	s_mov_b64 exec, s[0:1]
	s_mov_b64 s[2:3], 0
	v_lshrrev_b32_e32 v55, 6, v231
	s_sub_i32 s21, s76, 0x1c0
	s_lshl_b32 s21, s21, 2
	s_addk_i32 s21, 0x1d00
	v_add_u32_e32 v55, s21, v55
	s_branch .LBB0_1008
